# phase_post<64> row loop software-pipelined: next iteration's 20 ushort loads prefetched into v112-v131 after the conversions, vmcnt(20) on the back edge
# baseline (speedup 1.0000x reference)
; DI float bf2f(bf16 b) { return __uint_as_float(((unsigned)b) << 16); }
;     ...
;     const int gw = blockIdx.x * 8 + wave, NGW = gridDim.x * 8;
;     float gq0, gq1 = 0.f, gk0, gk1 = 0.f;
;     gq0 = qg[lane]; gk0 = kg[lane]; if (HD == 128) { gq1 = qg[lane + 64]; gk1 = kg[lane + 64]; }
;     const int jj = (HD == 64) ? (lane & 31) : lane;
;     const float invf = exp2f(-(float)(jj & (PPA - 1)) * (13.287712379549449f / (float)PPA));
;     for (int row0 = row_lo + gw; row0 < row_hi; row0 += R * NGW) {
;         int rows[R]; bool ok[R], lat[R]; int h0[R]; float cs[R], sn[R]; bf16* base[R];
;         float x1[R][NH], x2[R][NH], ss[R][NH];
; #pragma unroll
;         for (int q = 0; q < R; ++q) { rows[q] = row0 + q * NGW; ok[q] = rows[q] < row_hi; if (!ok[q]) rows[q] = row0;
;             lat[q] = rows[q] >= NCTX; const int tt = (rows[q] - NCTX) & (SEQ - 1);
;             cs[q] = 1.f; sn[q] = 0.f;
;             if (lat[q]) { const float ang = (float)(jj < PPA ? (tt >> 6) : (tt & 63)) * invf; cs[q] = __cosf(ang); sn[q] = __sinf(ang); }
;             h0[q] = (lat[q] || q_for_ctx) ? 0 : nq;
;             base[q] = QKV + (size_t)rows[q] * pitch + qcol;
; #pragma unroll
;             for (int hq = 0; hq < NH; ++hq) { x1[q][hq] = bf2f(base[q][hq * HD + lane]); x2[q][hq] = 0.f; if (HD == 128) x2[q][hq] = bf2f(base[q][hq * HD + lane + 64]); } }
.LBB0_251:
	s_or_b64 exec, exec, s[0:1]
	s_waitcnt lgkmcnt(0)
	s_barrier
	v_mbcnt_lo_u32_b32 v0, -1, 0
	v_mbcnt_hi_u32_b32 v0, -1, v0
	s_andn2_b64 vcc, exec, s[38:39]
	v_add_u32_e32 v16, s86, v0
	s_nop 0
	v_and_b32_e32 v0, 63, v16
	s_cbranch_vccnz .LBB0_278
	v_readlane_b32 s0, v253, 29
	v_lshlrev_b32_e32 v1, 2, v0
	v_readlane_b32 s8, v253, 37
	v_readlane_b32 s9, v253, 38
	v_readlane_b32 s6, v253, 35
	v_readlane_b32 s7, v253, 36
	s_nop 2
	global_load_dword v5, v1, s[8:9]
	s_nop 0
	global_load_dword v17, v1, s[6:7]
	v_and_b32_e32 v1, 15, v16
	v_cvt_f32_ubyte0_e32 v1, v1
	v_mul_f32_e32 v2, 0xbf549a78, v1
	s_mov_b32 s0, 0xc2fc0000
	v_mov_b32_e32 v3, 0x42800000
	v_cmp_gt_f32_e32 vcc, s0, v2
	v_readlane_b32 s2, v253, 31
	v_readlane_b32 s3, v253, 32
	v_cndmask_b32_e32 v2, 0, v3, vcc
	v_fmac_f32_e32 v2, 0xbf549a78, v1
	v_exp_f32_e32 v1, v2
	v_not_b32_e32 v2, 63
	v_cndmask_b32_e32 v2, 0, v2, vcc
	v_or_b32_e32 v10, 64, v0
	v_readlane_b32 s2, v253, 63
	v_readlane_b32 s1, v253, 30
	v_ldexp_f32 v33, v1, v2
	v_and_b32_e32 v1, 16, v16
	v_mov_b32_e32 v2, 0
	v_or_b32_e32 v14, 0x80, v0
	v_or_b32_e32 v18, 0xc0, v0
	v_or_b32_e32 v20, 0x100, v0
	v_or_b32_e32 v22, 0x140, v0
	v_or_b32_e32 v24, 0x180, v0
	v_or_b32_e32 v26, 0x1c0, v0
	v_or_b32_e32 v28, 0x200, v0
	v_or_b32_e32 v30, 0x240, v0
	v_lshlrev_b32_e32 v6, 1, v0
	v_lshlrev_b32_e32 v10, 1, v10
	v_readlane_b32 s3, v252, 0
	v_cmp_eq_u32_e64 s[34:35], 0, v1
	v_cmp_gt_u32_e64 s[36:37], 32, v0
	v_mov_b32_e32 v4, 1.0
	v_mov_b32_e32 v8, v6
	v_mov_b32_e32 v9, v2
	v_mov_b32_e32 v12, v10
	v_mov_b32_e32 v13, v2
	v_lshlrev_b32_e32 v14, 1, v14
	v_lshlrev_b32_e32 v18, 1, v18
	v_lshlrev_b32_e32 v20, 1, v20
	v_lshlrev_b32_e32 v22, 1, v22
	v_lshlrev_b32_e32 v24, 1, v24
	v_lshlrev_b32_e32 v26, 1, v26
	v_lshlrev_b32_e32 v28, 1, v28
	v_lshlrev_b32_e32 v30, 1, v30
	v_mov_b32_e32 v35, 0x358637bd
	s_mov_b32 s0, 0x3c800000
	s_mov_b32 s1, 0x800000
	v_mov_b32_e32 v15, v2
	v_mov_b32_e32 v19, v2
	v_mov_b32_e32 v21, v2
	v_mov_b32_e32 v23, v2
	v_mov_b32_e32 v25, v2
	v_mov_b32_e32 v27, v2
	v_mov_b32_e32 v29, v2
	v_mov_b32_e32 v31, v2
	v_mbcnt_hi_u32_b32 v74, -1, v216
	s_mov_b32 s3, s2
	s_mov_b32 s8, 0x358637bd
	v_readlane_b32 s4, v253, 33
	v_readlane_b32 s5, v253, 34
	v_readlane_b32 s10, v253, 39
	v_readlane_b32 s11, v253, 40
	v_readlane_b32 s12, v253, 41
	v_readlane_b32 s13, v253, 42
	v_readlane_b32 s14, v253, 43
	v_readlane_b32 s15, v253, 44
	s_mul_i32 s100, s3, 0x1600
	s_mul_hi_i32 s101, s3, 0x1600
	s_add_u32 s100, s82, s100
	s_addc_u32 s101, s83, s101
	s_add_u32 s100, s100, 0x1000
	s_addc_u32 s101, s101, 0
	global_load_ushort v112, v6, s[100:101]
	global_load_ushort v113, v20, s[100:101]
	global_load_ushort v114, v22, s[100:101]
	global_load_ushort v115, v24, s[100:101]
	global_load_ushort v116, v26, s[100:101]
	global_load_ushort v117, v28, s[100:101]
	global_load_ushort v118, v30, s[100:101]
	global_load_ushort v119, v10, s[100:101]
	global_load_ushort v120, v14, s[100:101]
	global_load_ushort v121, v18, s[100:101]
	s_add_i32 s99, s3, s54
	s_cmp_lt_i32 s99, 0x8800
	s_cselect_b32 s99, s99, s3
	s_mul_i32 s100, s99, 0x1600
	s_mul_hi_i32 s101, s99, 0x1600
	s_add_u32 s100, s82, s100
	s_addc_u32 s101, s83, s101
	s_add_u32 s100, s100, 0x1000
	s_addc_u32 s101, s101, 0
	global_load_ushort v122, v6, s[100:101]
	global_load_ushort v123, v30, s[100:101]
	global_load_ushort v124, v28, s[100:101]
	global_load_ushort v125, v10, s[100:101]
	global_load_ushort v126, v14, s[100:101]
	global_load_ushort v127, v18, s[100:101]
	global_load_ushort v128, v20, s[100:101]
	global_load_ushort v129, v22, s[100:101]
	global_load_ushort v130, v24, s[100:101]
	global_load_ushort v131, v26, s[100:101]
	s_waitcnt vmcnt(0)
	s_branch .LBB0_254
.LBB0_253:
	s_add_i32 s3, s2, s54
	s_cmp_gt_i32 s3, 0x87ff
	s_cbranch_scc1 .LBB0_278
	s_waitcnt vmcnt(20)

; DI float bf2f(bf16 b) { return __uint_as_float(((unsigned)b) << 16); }
;     ...
;     for (int row0 = row_lo + gw; row0 < row_hi; row0 += R * NGW) {
;         int rows[R]; bool ok[R], lat[R]; int h0[R]; float cs[R], sn[R]; bf16* base[R];
;         float x1[R][NH], x2[R][NH], ss[R][NH];
; #pragma unroll
;         for (int q = 0; q < R; ++q) { rows[q] = row0 + q * NGW; ok[q] = rows[q] < row_hi; if (!ok[q]) rows[q] = row0;
;             lat[q] = rows[q] >= NCTX; const int tt = (rows[q] - NCTX) & (SEQ - 1);
;             cs[q] = 1.f; sn[q] = 0.f;
;             if (lat[q]) { const float ang = (float)(jj < PPA ? (tt >> 6) : (tt & 63)) * invf; cs[q] = __cosf(ang); sn[q] = __sinf(ang); }
;             h0[q] = (lat[q] || q_for_ctx) ? 0 : nq;
;             base[q] = QKV + (size_t)rows[q] * pitch + qcol;
; #pragma unroll
;             for (int hq = 0; hq < NH; ++hq) { x1[q][hq] = bf2f(base[q][hq * HD + lane]); x2[q][hq] = 0.f; if (HD == 128) x2[q][hq] = bf2f(base[q][hq * HD + lane + 64]); } }
;         asm volatile("" ::: "memory");
; #pragma unroll
;         for (int q = 0; q < R; ++q)
; #pragma unroll
;             for (int hq = 0; hq < NH; ++hq) ss[q][hq] = x1[q][hq] * x1[q][hq] + x2[q][hq] * x2[q][hq];
; #pragma unroll
;         for (int o = 1; o < 64; o <<= 1) {
; #pragma unroll
;             for (int q = 0; q < R; ++q)
; #pragma unroll
;                 for (int hq = 0; hq < NH; ++hq) ss[q][hq] += __shfl_xor(ss[q][hq], o); }
.LBB0_256:
	s_mul_i32 s4, s3, 0x1600
	s_mul_hi_i32 s2, s3, 0x1600
	s_add_u32 s4, s82, s4
	s_addc_u32 s2, s83, s2
	s_add_u32 s4, s4, 0x1000
	s_addc_u32 s5, s2, 0
	s_waitcnt lgkmcnt(0)
	s_add_i32 s2, s3, s54
	s_cmp_lt_i32 s2, 0x8800
	s_cselect_b64 s[6:7], -1, 0
	v_lshl_add_u64 v[62:63], s[4:5], 0, v[8:9]
	v_lshl_add_u64 v[58:59], s[4:5], 0, v[12:13]
	v_lshl_add_u64 v[56:57], s[4:5], 0, v[14:15]
	v_lshl_add_u64 v[52:53], s[4:5], 0, v[18:19]
	v_lshl_add_u64 v[50:51], s[4:5], 0, v[20:21]
	v_lshl_add_u64 v[46:47], s[4:5], 0, v[22:23]
	v_lshl_add_u64 v[42:43], s[4:5], 0, v[24:25]
	v_lshl_add_u64 v[40:41], s[4:5], 0, v[26:27]
	v_lshl_add_u64 v[38:39], s[4:5], 0, v[28:29]
	v_lshl_add_u64 v[36:37], s[4:5], 0, v[30:31]
	s_and_b64 s[4:5], s[6:7], exec
	s_cselect_b32 s3, s2, s3
	s_cmpk_lt_i32 s3, 0x800
	v_mov_b32_e32 v1, v4
	v_mov_b32_e32 v3, v2
	s_cbranch_scc1 .LBB0_258
	s_bfe_u32 s4, s3, 0x60006
	s_xor_b32 s4, s4, 32
	s_and_b32 s5, s3, 63
	v_mov_b32_e32 v1, s5
	v_mov_b32_e32 v3, s4
	v_cndmask_b32_e64 v1, v1, v3, s[34:35]
	v_cvt_f32_ubyte0_e32 v1, v1
	v_mul_f32_e32 v1, v33, v1
	v_mul_f32_e32 v3, 0.15915494, v1
	v_cos_f32_e32 v1, v3
	v_sin_f32_e32 v3, v3
.LBB0_258:
	s_mul_hi_i32 s4, s3, 0x1600
	s_mulk_i32 s3, 0x1600
	s_add_u32 s3, s82, s3
	s_addc_u32 s5, s83, s4
	s_add_u32 s4, s3, 0x1000
	s_addc_u32 s5, s5, 0
	v_lshlrev_b32_e32 v90, 16, v112
	v_and_b32_e32 v7, 64, v74
	v_lshlrev_b32_e32 v60, 16, v113
	v_xor_b32_e32 v11, 1, v74
	v_add_u32_e32 v92, 64, v7
	v_lshlrev_b32_e32 v61, 16, v121
	v_lshlrev_b32_e32 v55, 16, v114
	v_xor_b32_e32 v44, 2, v74
	v_cmp_lt_i32_e32 vcc, v11, v92
	v_mul_f32_e32 v72, v90, v90
	v_lshlrev_b32_e32 v66, 16, v120
	v_cndmask_b32_e32 v7, v74, v11, vcc
	v_cmp_lt_i32_e32 vcc, v44, v92
	v_lshlrev_b32_e32 v93, 2, v7
	v_lshlrev_b32_e32 v54, 16, v115
	v_cndmask_b32_e32 v11, v74, v44, vcc
	v_lshlrev_b32_e32 v7, 2, v11
	ds_bpermute_b32 v11, v93, v72
	v_pk_mul_f32 v[68:69], v[60:61], v[60:61]
	v_pk_mul_f32 v[70:71], v[54:55], v[54:55]
	ds_bpermute_b32 v72, v93, v68
	ds_bpermute_b32 v68, v93, v70
	s_waitcnt lgkmcnt(2)
	v_fmac_f32_e32 v11, v90, v90
	ds_bpermute_b32 v44, v7, v11
	ds_bpermute_b32 v73, v93, v69
	ds_bpermute_b32 v69, v93, v71
	v_lshlrev_b32_e32 v67, 16, v119
	v_lshlrev_b32_e32 v49, 16, v116
	s_waitcnt lgkmcnt(2)
	v_add_f32_e32 v70, v11, v44
	v_lshlrev_b32_e32 v48, 16, v117
	v_lshlrev_b32_e32 v45, 16, v118
	v_pk_mul_f32 v[64:65], v[66:67], v[66:67]
	v_pk_mul_f32 v[76:77], v[48:49], v[48:49]
	ds_bpermute_b32 v104, v93, v64
	ds_bpermute_b32 v64, v93, v76
	ds_bpermute_b32 v105, v93, v65
	ds_bpermute_b32 v65, v93, v77
	v_lshlrev_b32_e32 v44, 16, v122
	v_lshlrev_b32_e32 v75, 16, v123
	v_lshlrev_b32_e32 v76, 16, v124
	v_lshlrev_b32_e32 v11, 16, v125
	v_mul_f32_e32 v71, v11, v11
	ds_bpermute_b32 v71, v93, v71
	v_lshlrev_b32_e32 v84, 16, v126
	v_lshlrev_b32_e32 v79, 16, v129
	v_mul_f32_e32 v86, v79, v79
	ds_bpermute_b32 v86, v93, v86
	s_waitcnt lgkmcnt(1)
	v_fmac_f32_e32 v71, v11, v11
	v_lshlrev_b32_e32 v81, 16, v127
	v_lshlrev_b32_e32 v80, 16, v128
	ds_bpermute_b32 v94, v7, v71
	v_mul_f32_e32 v82, v84, v84
	v_mul_f32_e32 v85, v80, v80
	ds_bpermute_b32 v82, v93, v82
	ds_bpermute_b32 v85, v93, v85
	s_waitcnt lgkmcnt(3)
	v_fmac_f32_e32 v86, v79, v79
	v_lshlrev_b32_e32 v78, 16, v130
	v_mul_f32_e32 v83, v81, v81
	s_waitcnt lgkmcnt(2)
	v_add_f32_e32 v71, v71, v94
	ds_bpermute_b32 v94, v7, v86
	v_mul_f32_e32 v87, v78, v78
	v_mul_f32_e32 v89, v76, v76
	ds_bpermute_b32 v83, v93, v83
	ds_bpermute_b32 v87, v93, v87
	ds_bpermute_b32 v89, v93, v89
	s_waitcnt lgkmcnt(5)
	v_fmac_f32_e32 v82, v84, v84
	s_waitcnt lgkmcnt(4)
	v_fmac_f32_e32 v85, v80, v80
	ds_bpermute_b32 v95, v7, v82
	ds_bpermute_b32 v97, v7, v85
	s_waitcnt lgkmcnt(5)
	v_add_f32_e32 v86, v86, v94
	v_xor_b32_e32 v94, 4, v74
	s_waitcnt lgkmcnt(4)
	v_fmac_f32_e32 v83, v81, v81
	v_cmp_lt_i32_e32 vcc, v94, v92
	s_waitcnt lgkmcnt(3)
	v_fmac_f32_e32 v87, v78, v78
	s_waitcnt lgkmcnt(2)
	v_fmac_f32_e32 v89, v76, v76
	ds_bpermute_b32 v96, v7, v83
	v_cndmask_b32_e32 v94, v74, v94, vcc
	v_mul_f32_e32 v91, v75, v75
	s_waitcnt lgkmcnt(2)
	v_add_f32_e32 v82, v82, v95
	s_waitcnt lgkmcnt(1)
	v_add_f32_e32 v85, v85, v97
	ds_bpermute_b32 v95, v7, v87
	ds_bpermute_b32 v97, v7, v89
	v_lshlrev_b32_e32 v103, 2, v94
	ds_bpermute_b32 v91, v93, v91
	ds_bpermute_b32 v94, v103, v70
	v_lshlrev_b32_e32 v77, 16, v131
	s_add_i32 s98, s2, s54
	s_cmp_gt_i32 s98, 0x87ff
	s_cbranch_scc1 .LPOSTPF_skip
	s_mul_i32 s100, s98, 0x1600
	s_mul_hi_i32 s101, s98, 0x1600
	s_add_u32 s100, s82, s100
	s_addc_u32 s101, s83, s101
	s_add_u32 s100, s100, 0x1000
	s_addc_u32 s101, s101, 0
	global_load_ushort v112, v6, s[100:101]
	global_load_ushort v113, v20, s[100:101]
	global_load_ushort v114, v22, s[100:101]
	global_load_ushort v115, v24, s[100:101]
	global_load_ushort v116, v26, s[100:101]
	global_load_ushort v117, v28, s[100:101]
	global_load_ushort v118, v30, s[100:101]
	global_load_ushort v119, v10, s[100:101]
	global_load_ushort v120, v14, s[100:101]
	global_load_ushort v121, v18, s[100:101]
	s_add_i32 s99, s98, s54
	s_cmp_lt_i32 s99, 0x8800
	s_cselect_b32 s99, s99, s98
	s_mul_i32 s100, s99, 0x1600
	s_mul_hi_i32 s101, s99, 0x1600
	s_add_u32 s100, s82, s100
	s_addc_u32 s101, s83, s101
	s_add_u32 s100, s100, 0x1000
	s_addc_u32 s101, s101, 0
	global_load_ushort v122, v6, s[100:101]
	global_load_ushort v123, v30, s[100:101]
	global_load_ushort v124, v28, s[100:101]
	global_load_ushort v125, v10, s[100:101]
	global_load_ushort v126, v14, s[100:101]
	global_load_ushort v127, v18, s[100:101]
	global_load_ushort v128, v20, s[100:101]
	global_load_ushort v129, v22, s[100:101]
	global_load_ushort v130, v24, s[100:101]
	global_load_ushort v131, v26, s[100:101]
; DI bf16 f2bf(float x) { return (bf16)(cvtpk(x, 0.f) & 0xffffu); }
;     ...
;         for (int o = 1; o < 64; o <<= 1) {
; #pragma unroll
;             for (int q = 0; q < R; ++q)
; #pragma unroll
;                 for (int hq = 0; hq < NH; ++hq) ss[q][hq] += __shfl_xor(ss[q][hq], o); }
; #pragma unroll
;         for (int q = 0; q < R; ++q) {
; #pragma unroll
;             for (int hq = 0; hq < NH; ++hq) if (hq >= h0[q]) {
;                 const float rs = rsqrtf(ss[q][hq] * (1.f / (float)HD) + EPS);
;                 if (HD == 64) { const float y = x1[q][hq] * rs * (hq < 8 ? gq0 : gk0); const float pr = __shfl_xor(y, 32);
;                     if (ok[q]) base[q][hq * HD + lane] = f2bf(lane < 32 ? y * cs[q] - pr * sn[q] : y * cs[q] + pr * sn[q]); }
;                 else { const float y1 = x1[q][hq] * rs * (hq < 8 ? gq0 : gk0), y2 = x2[q][hq] * rs * (hq < 8 ? gq1 : gk1);
;                     if (ok[q]) { base[q][hq * HD + lane] = f2bf(y1 * cs[q] - y2 * sn[q]); base[q][hq * HD + lane + 64] = f2bf(y2 * cs[q] + y1 * sn[q]); } }
.LPOSTPF_skip:
	v_mul_f32_e32 v88, v77, v77
	s_waitcnt lgkmcnt(4)
	v_add_f32_e32 v83, v83, v96
	ds_bpermute_b32 v88, v93, v88
	s_waitcnt lgkmcnt(4)
	v_add_f32_e32 v87, v87, v95
	s_waitcnt lgkmcnt(3)
	v_add_f32_e32 v89, v89, v97
	ds_bpermute_b32 v95, v103, v71
	ds_bpermute_b32 v97, v103, v83
	s_waitcnt lgkmcnt(4)
	v_fmac_f32_e32 v91, v75, v75
	s_waitcnt lgkmcnt(3)
	v_add_f32_e32 v70, v70, v94
	ds_bpermute_b32 v94, v103, v86
	ds_bpermute_b32 v98, v7, v91
	s_waitcnt lgkmcnt(4)
	v_fmac_f32_e32 v88, v77, v77
	s_waitcnt lgkmcnt(3)
	v_add_f32_e32 v71, v71, v95
	s_waitcnt lgkmcnt(2)
	v_add_f32_e32 v83, v83, v97
	ds_bpermute_b32 v95, v103, v87
	ds_bpermute_b32 v97, v103, v89
	ds_bpermute_b32 v96, v7, v88
	s_waitcnt lgkmcnt(4)
	v_add_f32_e32 v86, v86, v94
	v_xor_b32_e32 v94, 8, v74
	s_waitcnt lgkmcnt(3)
	v_add_f32_e32 v91, v91, v98
	ds_bpermute_b32 v98, v103, v85
	v_cmp_lt_i32_e32 vcc, v94, v92
	s_waitcnt lgkmcnt(3)
	v_add_f32_e32 v87, v87, v95
	s_waitcnt lgkmcnt(2)
	v_add_f32_e32 v89, v89, v97
	v_cndmask_b32_e32 v94, v74, v94, vcc
	v_lshlrev_b32_e32 v106, 2, v94
	ds_bpermute_b32 v95, v106, v71
	ds_bpermute_b32 v97, v106, v83
	s_waitcnt lgkmcnt(3)
	v_add_f32_e32 v88, v88, v96
	ds_bpermute_b32 v96, v103, v82
	s_waitcnt lgkmcnt(3)
	v_add_f32_e32 v85, v85, v98
	ds_bpermute_b32 v98, v103, v91
	s_waitcnt lgkmcnt(3)
	v_add_f32_e32 v71, v71, v95
	s_waitcnt lgkmcnt(2)
	v_add_f32_e32 v83, v83, v97
	ds_bpermute_b32 v95, v106, v87
	ds_bpermute_b32 v97, v106, v89
	s_waitcnt lgkmcnt(3)
	v_add_f32_e32 v82, v82, v96
	ds_bpermute_b32 v96, v103, v88
	s_waitcnt lgkmcnt(3)
	v_add_f32_e32 v91, v91, v98
	ds_bpermute_b32 v94, v106, v70
	ds_bpermute_b32 v98, v106, v85
	s_waitcnt lgkmcnt(4)
	v_add_f32_e32 v87, v87, v95
	s_waitcnt lgkmcnt(3)
	v_add_f32_e32 v95, v89, v97
	v_xor_b32_e32 v89, 16, v74
	s_waitcnt lgkmcnt(2)
	v_add_f32_e32 v88, v88, v96
	ds_bpermute_b32 v96, v106, v82
	v_cmp_lt_i32_e32 vcc, v89, v92
	s_waitcnt lgkmcnt(2)
	v_add_f32_e32 v70, v70, v94
	s_waitcnt lgkmcnt(1)
	v_add_f32_e32 v85, v85, v98
	ds_bpermute_b32 v94, v106, v86
	ds_bpermute_b32 v98, v106, v91
	v_cndmask_b32_e32 v89, v74, v89, vcc
	v_lshlrev_b32_e32 v107, 2, v89
	ds_bpermute_b32 v89, v107, v70
	s_waitcnt lgkmcnt(3)
	v_add_f32_e32 v82, v82, v96
	ds_bpermute_b32 v96, v106, v88
	s_waitcnt lgkmcnt(3)
	v_add_f32_e32 v86, v86, v94
	s_waitcnt lgkmcnt(2)
	v_add_f32_e32 v97, v91, v98
	ds_bpermute_b32 v91, v107, v71
	ds_bpermute_b32 v94, v107, v82
	s_waitcnt lgkmcnt(3)
	v_add_f32_e32 v108, v70, v89
	ds_bpermute_b32 v70, v107, v86
	s_waitcnt lgkmcnt(3)
	v_add_f32_e32 v88, v88, v96
	s_waitcnt lgkmcnt(2)
	v_add_f32_e32 v100, v71, v91
	s_waitcnt lgkmcnt(1)
	v_add_f32_e32 v96, v82, v94
	ds_bpermute_b32 v71, v107, v87
	ds_bpermute_b32 v82, v107, v88
	s_waitcnt lgkmcnt(2)
	v_add_f32_e32 v89, v86, v70
	v_xor_b32_e32 v70, 32, v74
	v_cmp_lt_i32_e32 vcc, v70, v92
	s_waitcnt lgkmcnt(1)
	v_add_f32_e32 v87, v87, v71
	s_waitcnt lgkmcnt(0)
	v_add_f32_e32 v86, v88, v82
	v_cndmask_b32_e32 v70, v74, v70, vcc
	v_lshlrev_b32_e32 v82, 2, v70
	v_pk_fma_f32 v[70:71], v[66:67], v[66:67], v[104:105]
	ds_bpermute_b32 v105, v7, v71
	ds_bpermute_b32 v104, v7, v70
	ds_bpermute_b32 v88, v82, v108
	ds_bpermute_b32 v98, v107, v83
	ds_bpermute_b32 v99, v107, v85
	ds_bpermute_b32 v102, v82, v100
	s_waitcnt lgkmcnt(4)
	v_pk_add_f32 v[70:71], v[70:71], v[104:105]
	ds_bpermute_b32 v105, v103, v71
	ds_bpermute_b32 v104, v103, v70
	s_waitcnt lgkmcnt(5)
	v_add_f32_e32 v88, v108, v88
	v_fmamk_f32 v88, v88, 0x3c800000, v35
	v_mul_f32_e32 v92, 0x4b800000, v88
	v_cmp_gt_f32_e32 vcc, s1, v88
	s_waitcnt lgkmcnt(0)
	v_pk_add_f32 v[70:71], v[70:71], v[104:105]
	ds_bpermute_b32 v105, v106, v71
	v_cndmask_b32_e32 v88, v88, v92, vcc
	v_rsq_f32_e32 v88, v88
	ds_bpermute_b32 v104, v106, v70
	v_add_f32_e32 v94, v83, v98
	ds_bpermute_b32 v83, v107, v95
	v_mul_f32_e32 v108, 0x45800000, v88
	v_cndmask_b32_e32 v88, v88, v108, vcc
	s_waitcnt lgkmcnt(1)
	v_pk_add_f32 v[70:71], v[70:71], v[104:105]
	v_mul_f32_e32 v88, v88, v90
	ds_bpermute_b32 v105, v107, v71
	ds_bpermute_b32 v104, v107, v70
	v_mul_f32_e32 v108, v17, v88
	ds_bpermute_b32 v109, v82, v108
	ds_bpermute_b32 v98, v107, v97
	v_add_f32_e32 v91, v85, v99
	s_waitcnt lgkmcnt(2)
	v_pk_add_f32 v[70:71], v[70:71], v[104:105]
	ds_bpermute_b32 v105, v82, v71
	ds_bpermute_b32 v104, v82, v70
	s_waitcnt lgkmcnt(3)
	v_mul_f32_e32 v109, v34, v109
	v_cndmask_b32_e64 v109, v109, -v109, s[36:37]
	v_fmac_f32_e32 v109, v32, v108
	v_cvt_pk_bf16_f32 v108, v109, s0
	global_store_short v[62:63], v108, off
	v_pk_fma_f32 v[62:63], v[60:61], v[60:61], v[72:73]
	s_waitcnt lgkmcnt(0)
	v_pk_add_f32 v[104:105], v[70:71], v[104:105]
	v_mov_b64_e32 v[70:71], s[8:9]
	ds_bpermute_b32 v73, v7, v63
	ds_bpermute_b32 v72, v7, v62
	v_pk_fma_f32 v[104:105], v[104:105], s[0:1], v[70:71] op_sel_hi:[1,0,0]
	v_add_f32_e32 v85, v95, v83
	v_mul_f32_e32 v110, 0x4b800000, v105
	v_cmp_gt_f32_e32 vcc, s1, v105
	s_waitcnt lgkmcnt(0)
	v_pk_add_f32 v[62:63], v[62:63], v[72:73]
	ds_bpermute_b32 v73, v103, v63
	v_cndmask_b32_e32 v105, v105, v110, vcc
	v_rsq_f32_e32 v105, v105
	ds_bpermute_b32 v72, v103, v62
	v_add_f32_e32 v83, v97, v98
	ds_bpermute_b32 v99, v82, v96
	v_mul_f32_e32 v108, 0x45800000, v105
	v_cndmask_b32_e32 v105, v105, v108, vcc
	v_mul_f32_e32 v67, v105, v67
	v_mul_f32_e32 v67, v17, v67
	s_waitcnt lgkmcnt(1)
	v_pk_add_f32 v[62:63], v[62:63], v[72:73]
	ds_bpermute_b32 v105, v82, v67
	ds_bpermute_b32 v73, v106, v63
	ds_bpermute_b32 v72, v106, v62
	v_mul_f32_e32 v108, 0x4b800000, v104
	v_cmp_gt_f32_e32 vcc, s1, v104
	s_waitcnt lgkmcnt(2)
	v_mul_f32_e32 v105, v34, v105
	v_cndmask_b32_e64 v105, v105, -v105, s[36:37]
	v_cndmask_b32_e32 v104, v104, v108, vcc
	v_rsq_f32_e32 v104, v104
	s_waitcnt lgkmcnt(0)
; DI bf16 f2bf(float x) { return (bf16)(cvtpk(x, 0.f) & 0xffffu); }
;     ...
;         for (int q = 0; q < R; ++q) {
; #pragma unroll
;             for (int hq = 0; hq < NH; ++hq) if (hq >= h0[q]) {
;                 const float rs = rsqrtf(ss[q][hq] * (1.f / (float)HD) + EPS);
;                 if (HD == 64) { const float y = x1[q][hq] * rs * (hq < 8 ? gq0 : gk0); const float pr = __shfl_xor(y, 32);
;                     if (ok[q]) base[q][hq * HD + lane] = f2bf(lane < 32 ? y * cs[q] - pr * sn[q] : y * cs[q] + pr * sn[q]); }
;                 else { const float y1 = x1[q][hq] * rs * (hq < 8 ? gq0 : gk0), y2 = x2[q][hq] * rs * (hq < 8 ? gq1 : gk1);
;                     if (ok[q]) { base[q][hq * HD + lane] = f2bf(y1 * cs[q] - y2 * sn[q]); base[q][hq * HD + lane + 64] = f2bf(y2 * cs[q] + y1 * sn[q]); } }
	v_pk_add_f32 v[62:63], v[62:63], v[72:73]
	ds_bpermute_b32 v73, v107, v63
	ds_bpermute_b32 v72, v107, v62
	v_fmac_f32_e32 v105, v32, v67
	v_mul_f32_e32 v67, 0x45800000, v104
	v_cndmask_b32_e32 v67, v104, v67, vcc
	v_mul_f32_e32 v66, v67, v66
	v_mul_f32_e32 v104, v17, v66
	ds_bpermute_b32 v108, v82, v104
	s_waitcnt lgkmcnt(1)
	v_pk_add_f32 v[62:63], v[62:63], v[72:73]
	ds_bpermute_b32 v67, v82, v63
	ds_bpermute_b32 v66, v82, v62
	v_cvt_pk_bf16_f32 v72, v105, s0
	global_store_short v[58:59], v72, off
	s_waitcnt lgkmcnt(2)
	v_mul_f32_e32 v58, v34, v108
	v_cndmask_b32_e64 v72, v58, -v58, s[36:37]
	s_waitcnt lgkmcnt(0)
	v_pk_add_f32 v[58:59], v[62:63], v[66:67]
	v_fmac_f32_e32 v72, v32, v104
	v_pk_fma_f32 v[58:59], v[58:59], s[0:1], v[70:71] op_sel_hi:[1,0,0]
	ds_bpermute_b32 v101, v82, v94
	v_mul_f32_e32 v62, 0x4b800000, v59
	v_cmp_gt_f32_e32 vcc, s1, v59
	ds_bpermute_b32 v98, v82, v91
	ds_bpermute_b32 v97, v82, v89
	v_cndmask_b32_e32 v59, v59, v62, vcc
	v_cvt_pk_bf16_f32 v62, v72, s0
	global_store_short v[56:57], v62, off
	v_pk_fma_f32 v[56:57], v[54:55], v[54:55], v[68:69]
	ds_bpermute_b32 v63, v7, v57
	ds_bpermute_b32 v62, v7, v56
	v_rsq_f32_e32 v59, v59
	ds_bpermute_b32 v95, v82, v87
	ds_bpermute_b32 v92, v82, v86
	ds_bpermute_b32 v90, v82, v85
	s_waitcnt lgkmcnt(3)
	v_pk_add_f32 v[56:57], v[56:57], v[62:63]
	ds_bpermute_b32 v63, v103, v57
	ds_bpermute_b32 v62, v103, v56
	v_mul_f32_e32 v66, 0x45800000, v59
	v_cndmask_b32_e32 v59, v59, v66, vcc
	v_mul_f32_e32 v59, v59, v61
	v_mul_f32_e32 v61, v17, v59
	v_mul_f32_e32 v59, 0x4b800000, v58
	v_cmp_gt_f32_e32 vcc, s1, v58
	s_waitcnt lgkmcnt(0)
	v_pk_add_f32 v[56:57], v[56:57], v[62:63]
	ds_bpermute_b32 v66, v82, v61
	v_cndmask_b32_e32 v58, v58, v59, vcc
	v_rsq_f32_e32 v67, v58
	ds_bpermute_b32 v59, v106, v57
	ds_bpermute_b32 v58, v106, v56
	s_waitcnt lgkmcnt(2)
	v_mul_f32_e32 v62, v34, v66
	v_cndmask_b32_e64 v62, v62, -v62, s[36:37]
	v_fmac_f32_e32 v62, v32, v61
	v_mul_f32_e32 v61, 0x45800000, v67
	s_waitcnt lgkmcnt(0)
	v_pk_add_f32 v[56:57], v[56:57], v[58:59]
	ds_bpermute_b32 v59, v107, v57
	ds_bpermute_b32 v58, v107, v56
	v_cndmask_b32_e32 v61, v67, v61, vcc
	v_mul_f32_e32 v60, v61, v60
	v_mul_f32_e32 v60, v17, v60
	ds_bpermute_b32 v61, v82, v60
	s_waitcnt lgkmcnt(1)
	v_pk_add_f32 v[56:57], v[56:57], v[58:59]
	ds_bpermute_b32 v59, v82, v57
	ds_bpermute_b32 v58, v82, v56
	v_cvt_pk_bf16_f32 v62, v62, s0
	global_store_short v[52:53], v62, off
	s_waitcnt lgkmcnt(2)
	v_mul_f32_e32 v52, v34, v61
	v_cndmask_b32_e64 v61, v52, -v52, s[36:37]
	s_waitcnt lgkmcnt(0)
	v_pk_add_f32 v[52:53], v[56:57], v[58:59]
	v_fmac_f32_e32 v61, v32, v60
	v_pk_fma_f32 v[52:53], v[52:53], s[0:1], v[70:71] op_sel_hi:[1,0,0]
	ds_bpermute_b32 v88, v82, v83
	v_mul_f32_e32 v56, 0x4b800000, v53
	v_cmp_gt_f32_e32 vcc, s1, v53
	s_nop 1
	v_cndmask_b32_e32 v53, v53, v56, vcc
	v_cvt_pk_bf16_f32 v56, v61, s0
	global_store_short v[50:51], v56, off
	v_pk_fma_f32 v[50:51], v[48:49], v[48:49], v[64:65]
	ds_bpermute_b32 v57, v7, v51
	ds_bpermute_b32 v56, v7, v50
	v_rsq_f32_e32 v53, v53
	s_waitcnt lgkmcnt(0)
	v_pk_add_f32 v[50:51], v[50:51], v[56:57]
	ds_bpermute_b32 v57, v103, v51
	ds_bpermute_b32 v56, v103, v50
	v_mul_f32_e32 v58, 0x45800000, v53
	v_cndmask_b32_e32 v53, v53, v58, vcc
	v_mul_f32_e32 v53, v53, v55
	v_mul_f32_e32 v55, v17, v53
	v_mul_f32_e32 v53, 0x4b800000, v52
	v_cmp_gt_f32_e32 vcc, s1, v52
	s_waitcnt lgkmcnt(0)
	v_pk_add_f32 v[50:51], v[50:51], v[56:57]
	ds_bpermute_b32 v58, v82, v55
	v_cndmask_b32_e32 v52, v52, v53, vcc
	v_rsq_f32_e32 v59, v52
	ds_bpermute_b32 v53, v106, v51
	ds_bpermute_b32 v52, v106, v50
	s_waitcnt lgkmcnt(2)
	v_mul_f32_e32 v56, v34, v58
	v_cndmask_b32_e64 v56, v56, -v56, s[36:37]
	v_fmac_f32_e32 v56, v32, v55
	v_mul_f32_e32 v55, 0x45800000, v59
	s_waitcnt lgkmcnt(0)
; DI bf16 f2bf(float x) { return (bf16)(cvtpk(x, 0.f) & 0xffffu); }
;     ...
;         for (int q = 0; q < R; ++q) {
; #pragma unroll
;             for (int hq = 0; hq < NH; ++hq) if (hq >= h0[q]) {
;                 const float rs = rsqrtf(ss[q][hq] * (1.f / (float)HD) + EPS);
;                 if (HD == 64) { const float y = x1[q][hq] * rs * (hq < 8 ? gq0 : gk0); const float pr = __shfl_xor(y, 32);
;                     if (ok[q]) base[q][hq * HD + lane] = f2bf(lane < 32 ? y * cs[q] - pr * sn[q] : y * cs[q] + pr * sn[q]); }
;                 else { const float y1 = x1[q][hq] * rs * (hq < 8 ? gq0 : gk0), y2 = x2[q][hq] * rs * (hq < 8 ? gq1 : gk1);
;                     if (ok[q]) { base[q][hq * HD + lane] = f2bf(y1 * cs[q] - y2 * sn[q]); base[q][hq * HD + lane + 64] = f2bf(y2 * cs[q] + y1 * sn[q]); } }
	v_pk_add_f32 v[50:51], v[50:51], v[52:53]
	ds_bpermute_b32 v53, v107, v51
	ds_bpermute_b32 v52, v107, v50
	v_cndmask_b32_e32 v55, v59, v55, vcc
	v_mul_f32_e32 v54, v55, v54
	v_mul_f32_e32 v54, v17, v54
	ds_bpermute_b32 v55, v82, v54
	s_waitcnt lgkmcnt(1)
	v_pk_add_f32 v[50:51], v[50:51], v[52:53]
	ds_bpermute_b32 v53, v82, v51
	ds_bpermute_b32 v52, v82, v50
	v_cvt_pk_bf16_f32 v56, v56, s0
	global_store_short v[46:47], v56, off
	s_waitcnt lgkmcnt(2)
	v_mul_f32_e32 v46, v34, v55
	v_cndmask_b32_e64 v55, v46, -v46, s[36:37]
	s_waitcnt lgkmcnt(0)
	v_pk_add_f32 v[46:47], v[50:51], v[52:53]
	v_pk_mul_f32 v[50:51], v[44:45], v[44:45]
	ds_bpermute_b32 v51, v93, v51
	ds_bpermute_b32 v50, v93, v50
	v_pk_fma_f32 v[46:47], v[46:47], s[0:1], v[70:71] op_sel_hi:[1,0,0]
	v_fmac_f32_e32 v55, v32, v54
	v_mul_f32_e32 v52, 0x4b800000, v47
	v_cmp_gt_f32_e32 vcc, s1, v47
	s_waitcnt lgkmcnt(0)
	v_pk_fma_f32 v[50:51], v[44:45], v[44:45], v[50:51]
	ds_bpermute_b32 v53, v7, v51
	v_cndmask_b32_e32 v47, v47, v52, vcc
	ds_bpermute_b32 v52, v7, v50
	v_cvt_pk_bf16_f32 v7, v55, s0
	global_store_short v[42:43], v7, off
	v_rsq_f32_e32 v47, v47
	s_waitcnt lgkmcnt(0)
	v_pk_add_f32 v[42:43], v[50:51], v[52:53]
	ds_bpermute_b32 v51, v103, v43
	ds_bpermute_b32 v50, v103, v42
	v_mul_f32_e32 v7, 0x45800000, v47
	v_cndmask_b32_e32 v7, v47, v7, vcc
	v_mul_f32_e32 v47, 0x4b800000, v46
	v_cmp_gt_f32_e32 vcc, s1, v46
	s_waitcnt lgkmcnt(0)
	v_pk_add_f32 v[42:43], v[42:43], v[50:51]
	ds_bpermute_b32 v51, v106, v43
	ds_bpermute_b32 v50, v106, v42
	v_cndmask_b32_e32 v46, v46, v47, vcc
	v_rsq_f32_e32 v52, v46
	v_mul_f32_e32 v7, v7, v49
	v_mul_f32_e32 v7, v17, v7
	s_waitcnt lgkmcnt(0)
	v_pk_add_f32 v[42:43], v[42:43], v[50:51]
	ds_bpermute_b32 v47, v107, v43
	ds_bpermute_b32 v46, v107, v42
	ds_bpermute_b32 v49, v82, v7
	s_waitcnt lgkmcnt(1)
	v_pk_add_f32 v[42:43], v[42:43], v[46:47]
	ds_bpermute_b32 v47, v82, v43
	ds_bpermute_b32 v46, v82, v42
	s_waitcnt lgkmcnt(2)
	v_mul_f32_e32 v49, v34, v49
	v_cndmask_b32_e64 v49, v49, -v49, s[36:37]
	v_fmac_f32_e32 v49, v32, v7
	v_mul_f32_e32 v7, 0x45800000, v52
	s_waitcnt lgkmcnt(0)
	v_pk_add_f32 v[42:43], v[42:43], v[46:47]
	v_cndmask_b32_e32 v7, v52, v7, vcc
	v_pk_fma_f32 v[42:43], v[42:43], s[0:1], v[70:71] op_sel_hi:[1,0,0]
	v_mul_f32_e32 v7, v7, v48
	v_mul_f32_e32 v46, 0x4b800000, v43
	v_cmp_gt_f32_e32 vcc, s1, v43
	v_mul_f32_e32 v7, v5, v7
	ds_bpermute_b32 v48, v82, v7
	v_cndmask_b32_e32 v43, v43, v46, vcc
	v_rsq_f32_e32 v43, v43
	v_cvt_pk_bf16_f32 v46, v49, s0
	global_store_short v[40:41], v46, off
	s_waitcnt lgkmcnt(0)
	v_mul_f32_e32 v40, v34, v48
	v_mul_f32_e32 v41, 0x45800000, v43
	v_cndmask_b32_e32 v41, v43, v41, vcc
	v_mul_f32_e32 v41, v41, v45
	v_mul_f32_e32 v41, v5, v41
	ds_bpermute_b32 v43, v82, v41
	v_cndmask_b32_e64 v40, v40, -v40, s[36:37]
	v_fmac_f32_e32 v40, v32, v7
	v_cvt_pk_bf16_f32 v7, v40, s0
	global_store_short v[38:39], v7, off
	s_waitcnt lgkmcnt(0)
	v_mul_f32_e32 v7, v34, v43
	v_mul_f32_e32 v34, 0x4b800000, v42
	v_cmp_gt_f32_e32 vcc, s1, v42
	v_cndmask_b32_e64 v7, v7, -v7, s[36:37]
	v_fmac_f32_e32 v7, v32, v41
	v_cndmask_b32_e32 v34, v42, v34, vcc
	v_rsq_f32_e32 v34, v34
	v_cndmask_b32_e64 v38, 0, 1, s[6:7]
	v_cvt_pk_bf16_f32 v7, v7, s0
	v_cmp_ne_u32_e64 s[38:39], 1, v38
	v_mul_f32_e32 v32, 0x45800000, v34
	v_cndmask_b32_e32 v32, v34, v32, vcc
	v_mul_f32_e32 v32, v32, v44
	v_mul_f32_e32 v32, v17, v32
	ds_bpermute_b32 v34, v82, v32
	s_andn2_b64 vcc, exec, s[6:7]
	global_store_short v[36:37], v7, off
	s_cbranch_vccnz .LBB0_260
	v_mov_b32_e32 v7, v2
	v_lshl_add_u64 v[36:37], s[4:5], 0, v[6:7]
	s_waitcnt lgkmcnt(0)
	v_mul_f32_e32 v7, v3, v34
	v_cndmask_b32_e64 v7, v7, -v7, s[36:37]
	v_fmac_f32_e32 v7, v1, v32
	v_cvt_pk_bf16_f32 v7, v7, s0
	global_store_short v[36:37], v7, off

; DI bf16 f2bf(float x) { return (bf16)(cvtpk(x, 0.f) & 0xffffu); }
;     ...
;             for (int hq = 0; hq < NH; ++hq) if (hq >= h0[q]) {
;                 const float rs = rsqrtf(ss[q][hq] * (1.f / (float)HD) + EPS);
;                 if (HD == 64) { const float y = x1[q][hq] * rs * (hq < 8 ? gq0 : gk0); const float pr = __shfl_xor(y, 32);
;                     if (ok[q]) base[q][hq * HD + lane] = f2bf(lane < 32 ? y * cs[q] - pr * sn[q] : y * cs[q] + pr * sn[q]); }
;                 else { const float y1 = x1[q][hq] * rs * (hq < 8 ? gq0 : gk0), y2 = x2[q][hq] * rs * (hq < 8 ? gq1 : gk1);
;                     if (ok[q]) { base[q][hq * HD + lane] = f2bf(y1 * cs[q] - y2 * sn[q]); base[q][hq * HD + lane + 64] = f2bf(y2 * cs[q] + y1 * sn[q]); } }
.LBB0_276:
	v_add_f32_e32 v7, v83, v88
	v_fmamk_f32 v7, v7, 0x3c800000, v35
	s_waitcnt lgkmcnt(0)
	v_mul_f32_e32 v11, 0x4b800000, v7
	v_cmp_gt_f32_e32 vcc, s1, v7
	s_nop 1
	v_cndmask_b32_e32 v7, v7, v11, vcc
	v_rsq_f32_e32 v7, v7
	s_nop 0
	v_mul_f32_e32 v11, 0x45800000, v7
	v_cndmask_b32_e32 v7, v7, v11, vcc
	v_mul_f32_e32 v7, v7, v75
	v_mul_f32_e32 v7, v5, v7
	ds_bpermute_b32 v11, v82, v7
	s_and_b64 vcc, exec, s[38:39]
	s_cbranch_vccnz .LBB0_253
	s_waitcnt lgkmcnt(0)
	v_mul_f32_e32 v3, v3, v11
	v_cndmask_b32_e64 v3, v3, -v3, s[36:37]
	v_fmac_f32_e32 v3, v1, v7
	v_lshl_add_u64 v[36:37], s[4:5], 0, v[30:31]
	v_cvt_pk_bf16_f32 v1, v3, s0
	global_store_short v[36:37], v1, off
	s_branch .LBB0_253
	s_nop 0
